# MLA (tiles by global_load_lds): waves 4-7 issue the next tile's transfers right behind their barrier
# speedup vs baseline: 1.0105x; 1.0105x over previous
; __device__ __forceinline__ void finishSM9(f32x16& p0, f32x16& p1, float alpha, float& l_reg, v8i32& p8) {
; #pragma unroll
;   for (int r = 0; r < 16; ++r) { p0[r] = __builtin_amdgcn_exp2f(p0[r]); p1[r] = __builtin_amdgcn_exp2f(p1[r]); }
;   float ps = 0;
; #pragma unroll
;   for (int r = 0; r < 16; ++r) ps += p0[r];
; #pragma unroll
;   for (int r = 0; r < 16; ++r) ps += p1[r];
;   { auto rr = __builtin_amdgcn_permlane32_swap(__float_as_uint(ps), __float_as_uint(ps), false, false);
;     ps = __uint_as_float(rr[0]) + __uint_as_float(rr[1]); }
;   l_reg = l_reg * alpha + ps;
; #pragma unroll
;   for (int g = 0; g < 4; ++g) {
;     int w = __builtin_amdgcn_cvt_pk_fp8_f32(p0[4 * g], p0[4 * g + 1], 0, false); p8[g] = __builtin_amdgcn_cvt_pk_fp8_f32(p0[4 * g + 2], p0[4 * g + 3], w, true);
;     int u = __builtin_amdgcn_cvt_pk_fp8_f32(p1[4 * g], p1[4 * g + 1], 0, false); p8[4 + g] = __builtin_amdgcn_cvt_pk_fp8_f32(p1[4 * g + 2], p1[4 * g + 3], u, true); }
; }
; __device__ __forceinline__ void pv8(f32x16* o, const char* Vt, const v8i32 p8, int r32, int hi) {
;   const int sw = (r32 >> 2) & 3, a0 = r32 * 64 + (((hi * 2) ^ sw) << 4), a1 = r32 * 64 + (((hi * 2 + 1) ^ sw) << 4);
; #pragma unroll
;   for (int d0 = 0; d0 < 4; ++d0) {
;     const v8i32 vf = cat8(*reinterpret_cast<const v4i32*>(Vt + d0 * 2048 + a0), *reinterpret_cast<const v4i32*>(Vt + d0 * 2048 + a1));
;     o[d0] = __builtin_amdgcn_mfma_scale_f32_32x32x64_f8f6f4(p8, vf, o[d0], 0, 0, 0, 127, 0, 127); }
; }
; __device__ __forceinline__ void qkt9(f32x16& p0, f32x16& p1, const char* Kn, const char* Kr, const v8i32* qf, const float init, int r32, int hi) {
; #pragma unroll
;   for (int r = 0; r < 16; ++r) { p0[r] = init; p1[r] = init; }
; #pragma unroll
;   for (int s = 0; s < 2; ++s) { const int c0 = s * 4 + hi * 2;
;     const v8i32 a0 = cat8(*reinterpret_cast<const v4i32*>(Kn + KN8SW(r32, c0)), *reinterpret_cast<const v4i32*>(Kn + KN8SW(r32, c0 + 1)));
;     const v8i32 a1 = cat8(*reinterpret_cast<const v4i32*>(Kn + 4096 + KN8SW(r32, c0)), *reinterpret_cast<const v4i32*>(Kn + 4096 + KN8SW(r32, c0 + 1)));
;     p0 = __builtin_amdgcn_mfma_scale_f32_32x32x64_f8f6f4(a0, qf[s], p0, 0, 0, 0, 127, 0, 124);
;     p1 = __builtin_amdgcn_mfma_scale_f32_32x32x64_f8f6f4(a1, qf[s], p1, 0, 0, 0, 127, 0, 124); }
;   { const int c0 = hi * 2;
.Lmla_stag_loop:
	ds_read_b128 v[114:117], v215 offset:24576
	ds_read_b128 v[118:121], v216 offset:24576
	ds_read_b128 v[222:225], v215 offset:28672
	ds_read_b128 v[226:229], v216 offset:28672
	v_exp_f32_e32 v0, v82
	v_exp_f32_e32 v177, v83
	v_exp_f32_e32 v179, v84
	v_exp_f32_e32 v254, v85
	v_add_f32_e32 v219, v0, v177
	v_cvt_pk_fp8_f32 v246, v0, v177
	v_add_f32_e32 v219, v179, v219
	v_add_f32_e32 v219, v254, v219
	v_cvt_pk_fp8_f32 v246, v179, v254 op_sel:[0,0,1]
	s_waitcnt lgkmcnt(2)
	v_mfma_scale_f32_32x32x64_f8f6f4 v[114:129], v[114:121], v[146:153], v[230:245], v194, v193 op_sel_hi:[0,0,0]
	v_exp_f32_e32 v0, v86
	v_exp_f32_e32 v177, v87
	v_exp_f32_e32 v179, v88
	v_exp_f32_e32 v254, v89
	v_add_f32_e32 v219, v0, v219
	v_add_f32_e32 v219, v177, v219
	v_cvt_pk_fp8_f32 v247, v0, v177
	v_add_f32_e32 v219, v179, v219
	v_add_f32_e32 v219, v254, v219
	v_cvt_pk_fp8_f32 v247, v179, v254 op_sel:[0,0,1]
	ds_read_b128 v[82:85], v213 offset:24576
	ds_read_b128 v[86:89], v214 offset:24576
	s_waitcnt lgkmcnt(2)
	v_mfma_scale_f32_32x32x64_f8f6f4 v[98:113], v[222:229], v[146:153], v[230:245], v194, v193 op_sel_hi:[0,0,0]
	ds_read_b128 v[222:225], v213 offset:28672
	ds_read_b128 v[226:229], v214 offset:28672
	v_exp_f32_e32 v0, v90
	v_exp_f32_e32 v177, v91
	v_exp_f32_e32 v179, v92
	v_exp_f32_e32 v254, v93
	v_add_f32_e32 v219, v0, v219
	v_add_f32_e32 v219, v177, v219
	v_cvt_pk_fp8_f32 v248, v0, v177
	v_add_f32_e32 v219, v179, v219
	v_add_f32_e32 v219, v254, v219
	v_cvt_pk_fp8_f32 v248, v179, v254 op_sel:[0,0,1]
	v_exp_f32_e32 v0, v94
	v_exp_f32_e32 v177, v95
	v_exp_f32_e32 v179, v96
	v_exp_f32_e32 v254, v97
	v_add_f32_e32 v219, v0, v219
	v_add_f32_e32 v219, v177, v219
	v_cvt_pk_fp8_f32 v249, v0, v177
	v_add_f32_e32 v219, v179, v219
	v_add_f32_e32 v219, v254, v219
	v_cvt_pk_fp8_f32 v249, v179, v254 op_sel:[0,0,1]
	ds_read_b128 v[90:93], v185 offset:36864
	ds_read_b128 v[94:97], v186 offset:36864
	s_waitcnt lgkmcnt(4)
	v_mfma_scale_f32_32x32x64_f8f6f4 v[114:129], v[82:89], v[138:145], v[114:129], v194, v193 op_sel_hi:[0,0,0]
	v_exp_f32_e32 v0, v66
	v_exp_f32_e32 v177, v67
	v_exp_f32_e32 v179, v68
	v_exp_f32_e32 v254, v69
	v_add_f32_e32 v219, v0, v219
	v_add_f32_e32 v219, v177, v219
	v_cvt_pk_fp8_f32 v250, v0, v177
	v_add_f32_e32 v219, v179, v219
	v_add_f32_e32 v219, v254, v219
	v_cvt_pk_fp8_f32 v250, v179, v254 op_sel:[0,0,1]
	s_waitcnt lgkmcnt(2)
	v_mfma_scale_f32_32x32x64_f8f6f4 v[98:113], v[222:229], v[138:145], v[98:113], v194, v193 op_sel_hi:[0,0,0]
	ds_read_b128 v[222:225], v185 offset:38912
	ds_read_b128 v[226:229], v186 offset:38912
	v_exp_f32_e32 v0, v70
	v_exp_f32_e32 v177, v71
	v_exp_f32_e32 v179, v72
	v_exp_f32_e32 v254, v73
	v_add_f32_e32 v219, v0, v219
	v_add_f32_e32 v219, v177, v219
	v_cvt_pk_fp8_f32 v251, v0, v177
	v_add_f32_e32 v219, v179, v219
	v_add_f32_e32 v219, v254, v219
	v_cvt_pk_fp8_f32 v251, v179, v254 op_sel:[0,0,1]
	v_exp_f32_e32 v0, v74
	v_exp_f32_e32 v177, v75
	v_exp_f32_e32 v179, v76
	v_exp_f32_e32 v254, v77
	v_add_f32_e32 v219, v0, v219
	v_add_f32_e32 v219, v177, v219
	v_cvt_pk_fp8_f32 v252, v0, v177
	v_add_f32_e32 v219, v179, v219
	v_add_f32_e32 v219, v254, v219
	v_cvt_pk_fp8_f32 v252, v179, v254 op_sel:[0,0,1]
	s_waitcnt lgkmcnt(2)
	v_mfma_scale_f32_32x32x64_f8f6f4 v[114:129], v[90:97], v[130:137], v[114:129], v194, v193 op_sel_hi:[0,0,0]
	v_exp_f32_e32 v0, v78
	v_exp_f32_e32 v177, v79
	v_exp_f32_e32 v179, v80
	v_exp_f32_e32 v254, v81
	v_add_f32_e32 v219, v0, v219
	v_add_f32_e32 v219, v177, v219
	v_cvt_pk_fp8_f32 v253, v0, v177
	v_add_f32_e32 v219, v179, v219
	v_add_f32_e32 v219, v254, v219
	v_cvt_pk_fp8_f32 v253, v179, v254 op_sel:[0,0,1]
	ds_read_b128 v[90:93], v185 offset:0
	ds_read_b128 v[94:97], v186 offset:0
	ds_read_b128 v[82:85], v185 offset:2048
	ds_read_b128 v[86:89], v186 offset:2048
	ds_read_b128 v[74:77], v185 offset:4096
	ds_read_b128 v[78:81], v186 offset:4096
	ds_read_b128 v[66:69], v185 offset:6144
	ds_read_b128 v[70:73], v186 offset:6144
	s_waitcnt lgkmcnt(8)
	v_mfma_scale_f32_32x32x64_f8f6f4 v[98:113], v[222:229], v[130:137], v[98:113], v194, v193 op_sel_hi:[0,0,0]
	v_mov_b32_e32 v0, v219
	s_nop 1
	v_permlane32_swap_b32_e32 v219, v0
	v_add_f32_e32 v219, v219, v0
	v_fma_f32 v209, v209, v218, v219
	v_max_f32_e32 v177, v114, v115
	v_max3_f32 v177, v177, v116, v117
	v_max3_f32 v177, v177, v118, v119
	v_max3_f32 v177, v177, v120, v121
	v_max3_f32 v177, v177, v122, v123
	v_max3_f32 v177, v177, v124, v125
	v_max3_f32 v177, v177, v126, v127
	v_max3_f32 v177, v177, v128, v129
	s_waitcnt lgkmcnt(6)
	v_mfma_scale_f32_32x32x64_f8f6f4 v[50:65], v[246:253], v[90:97], v[50:65], v194, v194 op_sel_hi:[0,0,0]
	s_waitcnt lgkmcnt(4)
	v_mfma_scale_f32_32x32x64_f8f6f4 v[34:49], v[246:253], v[82:89], v[34:49], v194, v194 op_sel_hi:[0,0,0]
	s_waitcnt vmcnt(0)
	s_waitcnt lgkmcnt(0)
	s_barrier
	s_add_i32 m0, s98, 0x0
	s_nop 0
	global_load_lds_dwordx4 v176, s[18:19]
	s_add_i32 m0, s98, 0x4000
	s_nop 0
	global_load_lds_dwordx4 v178, s[16:17]
	v_add_u32_e32 v176, 0x2000, v176
	v_add_u32_e32 v178, 0x20000, v178
	s_waitcnt lgkmcnt(2)
	v_mfma_scale_f32_32x32x64_f8f6f4 v[18:33], v[246:253], v[74:81], v[18:33], v194, v194 op_sel_hi:[0,0,0]
	s_waitcnt lgkmcnt(0)
	v_mfma_scale_f32_32x32x64_f8f6f4 v[2:17], v[246:253], v[66:73], v[2:17], v194, v194 op_sel_hi:[0,0,0]
	v_max_f32_e32 v0, v98, v99
	v_max3_f32 v0, v0, v100, v101
	v_max3_f32 v0, v0, v102, v103
	v_max3_f32 v0, v0, v104, v105
	v_max3_f32 v0, v0, v106, v107
	v_max3_f32 v0, v0, v108, v109
	v_max3_f32 v0, v0, v110, v111
	v_max3_f32 v0, v0, v112, v113
	v_max_f32_e32 v177, v177, v0
	v_mov_b32_e32 v0, v177
	v_mov_b32_e32 v221, 1.0
	s_nop 0
	v_permlane32_swap_b32_e32 v177, v0
	v_max_f32_e32 v177, v177, v0
	v_cmp_ge_f32_e32 vcc, s90, v177
	s_cmp_eq_u64 vcc, exec
	s_cbranch_scc0 .Lmla_s0_newmax
; __device__ __forceinline__ void finishSM9(f32x16& p0, f32x16& p1, float alpha, float& l_reg, v8i32& p8) {
; #pragma unroll
;   for (int r = 0; r < 16; ++r) { p0[r] = __builtin_amdgcn_exp2f(p0[r]); p1[r] = __builtin_amdgcn_exp2f(p1[r]); }
;   float ps = 0;
; #pragma unroll
;   for (int r = 0; r < 16; ++r) ps += p0[r];
; #pragma unroll
;   for (int r = 0; r < 16; ++r) ps += p1[r];
;   { auto rr = __builtin_amdgcn_permlane32_swap(__float_as_uint(ps), __float_as_uint(ps), false, false);
;     ps = __uint_as_float(rr[0]) + __uint_as_float(rr[1]); }
;   l_reg = l_reg * alpha + ps;
; #pragma unroll
;   for (int g = 0; g < 4; ++g) {
;     int w = __builtin_amdgcn_cvt_pk_fp8_f32(p0[4 * g], p0[4 * g + 1], 0, false); p8[g] = __builtin_amdgcn_cvt_pk_fp8_f32(p0[4 * g + 2], p0[4 * g + 3], w, true);
;     int u = __builtin_amdgcn_cvt_pk_fp8_f32(p1[4 * g], p1[4 * g + 1], 0, false); p8[4 + g] = __builtin_amdgcn_cvt_pk_fp8_f32(p1[4 * g + 2], p1[4 * g + 3], u, true); }
; }
; __device__ __forceinline__ void pv8(f32x16* o, const char* Vt, const v8i32 p8, int r32, int hi) {
;   const int sw = (r32 >> 2) & 3, a0 = r32 * 64 + (((hi * 2) ^ sw) << 4), a1 = r32 * 64 + (((hi * 2 + 1) ^ sw) << 4);
; #pragma unroll
;   for (int d0 = 0; d0 < 4; ++d0) {
;     const v8i32 vf = cat8(*reinterpret_cast<const v4i32*>(Vt + d0 * 2048 + a0), *reinterpret_cast<const v4i32*>(Vt + d0 * 2048 + a1));
;     o[d0] = __builtin_amdgcn_mfma_scale_f32_32x32x64_f8f6f4(p8, vf, o[d0], 0, 0, 0, 127, 0, 127); }
; }
; __device__ __forceinline__ void qkt9(f32x16& p0, f32x16& p1, const char* Kn, const char* Kr, const v8i32* qf, const float init, int r32, int hi) {
; #pragma unroll
;   for (int r = 0; r < 16; ++r) { p0[r] = init; p1[r] = init; }
; #pragma unroll
;   for (int s = 0; s < 2; ++s) { const int c0 = s * 4 + hi * 2;
;     const v8i32 a0 = cat8(*reinterpret_cast<const v4i32*>(Kn + KN8SW(r32, c0)), *reinterpret_cast<const v4i32*>(Kn + KN8SW(r32, c0 + 1)));
;     const v8i32 a1 = cat8(*reinterpret_cast<const v4i32*>(Kn + 4096 + KN8SW(r32, c0)), *reinterpret_cast<const v4i32*>(Kn + 4096 + KN8SW(r32, c0 + 1)));
;     p0 = __builtin_amdgcn_mfma_scale_f32_32x32x64_f8f6f4(a0, qf[s], p0, 0, 0, 0, 127, 0, 124);
;     p1 = __builtin_amdgcn_mfma_scale_f32_32x32x64_f8f6f4(a1, qf[s], p1, 0, 0, 0, 127, 0, 124); }
;   { const int c0 = hi * 2;
.Lmla_s0_cont:
	ds_read_b128 v[82:85], v215 offset:51200
	ds_read_b128 v[86:89], v216 offset:51200
	ds_read_b128 v[222:225], v215 offset:55296
	ds_read_b128 v[226:229], v216 offset:55296
	v_exp_f32_e32 v0, v114
	v_exp_f32_e32 v177, v115
	v_exp_f32_e32 v179, v116
	v_exp_f32_e32 v254, v117
	v_add_f32_e32 v219, v0, v177
	v_cvt_pk_fp8_f32 v246, v0, v177
	v_add_f32_e32 v219, v179, v219
	v_add_f32_e32 v219, v254, v219
	v_cvt_pk_fp8_f32 v246, v179, v254 op_sel:[0,0,1]
	s_waitcnt lgkmcnt(2)
	v_mfma_scale_f32_32x32x64_f8f6f4 v[82:97], v[82:89], v[146:153], v[230:245], v194, v193 op_sel_hi:[0,0,0]
	v_exp_f32_e32 v0, v118
	v_exp_f32_e32 v177, v119
	v_exp_f32_e32 v179, v120
	v_exp_f32_e32 v254, v121
	v_add_f32_e32 v219, v0, v219
	v_add_f32_e32 v219, v177, v219
	v_cvt_pk_fp8_f32 v247, v0, v177
	v_add_f32_e32 v219, v179, v219
	v_add_f32_e32 v219, v254, v219
	v_cvt_pk_fp8_f32 v247, v179, v254 op_sel:[0,0,1]
	ds_read_b128 v[114:117], v213 offset:51200
	ds_read_b128 v[118:121], v214 offset:51200
	s_waitcnt lgkmcnt(2)
	v_mfma_scale_f32_32x32x64_f8f6f4 v[66:81], v[222:229], v[146:153], v[230:245], v194, v193 op_sel_hi:[0,0,0]
	ds_read_b128 v[222:225], v213 offset:55296
	ds_read_b128 v[226:229], v214 offset:55296
	v_exp_f32_e32 v0, v122
	v_exp_f32_e32 v177, v123
	v_exp_f32_e32 v179, v124
	v_exp_f32_e32 v254, v125
	v_add_f32_e32 v219, v0, v219
	v_add_f32_e32 v219, v177, v219
	v_cvt_pk_fp8_f32 v248, v0, v177
	v_add_f32_e32 v219, v179, v219
	v_add_f32_e32 v219, v254, v219
	v_cvt_pk_fp8_f32 v248, v179, v254 op_sel:[0,0,1]
	v_exp_f32_e32 v0, v126
	v_exp_f32_e32 v177, v127
	v_exp_f32_e32 v179, v128
	v_exp_f32_e32 v254, v129
	v_add_f32_e32 v219, v0, v219
	v_add_f32_e32 v219, v177, v219
	v_cvt_pk_fp8_f32 v249, v0, v177
	v_add_f32_e32 v219, v179, v219
	v_add_f32_e32 v219, v254, v219
	v_cvt_pk_fp8_f32 v249, v179, v254 op_sel:[0,0,1]
	ds_read_b128 v[122:125], v185 offset:59392
	ds_read_b128 v[126:129], v186 offset:59392
	s_waitcnt lgkmcnt(4)
	v_mfma_scale_f32_32x32x64_f8f6f4 v[82:97], v[114:121], v[138:145], v[82:97], v194, v193 op_sel_hi:[0,0,0]
	v_exp_f32_e32 v0, v98
	v_exp_f32_e32 v177, v99
	v_exp_f32_e32 v179, v100
	v_exp_f32_e32 v254, v101
	v_add_f32_e32 v219, v0, v219
	v_add_f32_e32 v219, v177, v219
	v_cvt_pk_fp8_f32 v250, v0, v177
	v_add_f32_e32 v219, v179, v219
	v_add_f32_e32 v219, v254, v219
	v_cvt_pk_fp8_f32 v250, v179, v254 op_sel:[0,0,1]
	s_waitcnt lgkmcnt(2)
	v_mfma_scale_f32_32x32x64_f8f6f4 v[66:81], v[222:229], v[138:145], v[66:81], v194, v193 op_sel_hi:[0,0,0]
	ds_read_b128 v[222:225], v185 offset:61440
	ds_read_b128 v[226:229], v186 offset:61440
	v_exp_f32_e32 v0, v102
	v_exp_f32_e32 v177, v103
	v_exp_f32_e32 v179, v104
	v_exp_f32_e32 v254, v105
	v_add_f32_e32 v219, v0, v219
	v_add_f32_e32 v219, v177, v219
	v_cvt_pk_fp8_f32 v251, v0, v177
	v_add_f32_e32 v219, v179, v219
	v_add_f32_e32 v219, v254, v219
	v_cvt_pk_fp8_f32 v251, v179, v254 op_sel:[0,0,1]
	v_exp_f32_e32 v0, v106
	v_exp_f32_e32 v177, v107
	v_exp_f32_e32 v179, v108
	v_exp_f32_e32 v254, v109
	v_add_f32_e32 v219, v0, v219
	v_add_f32_e32 v219, v177, v219
	v_cvt_pk_fp8_f32 v252, v0, v177
	v_add_f32_e32 v219, v179, v219
	v_add_f32_e32 v219, v254, v219
	v_cvt_pk_fp8_f32 v252, v179, v254 op_sel:[0,0,1]
	s_waitcnt lgkmcnt(2)
	v_mfma_scale_f32_32x32x64_f8f6f4 v[82:97], v[122:129], v[130:137], v[82:97], v194, v193 op_sel_hi:[0,0,0]
	v_exp_f32_e32 v0, v110
	v_exp_f32_e32 v177, v111
	v_exp_f32_e32 v179, v112
	v_exp_f32_e32 v254, v113
	v_add_f32_e32 v219, v0, v219
	v_add_f32_e32 v219, v177, v219
	v_cvt_pk_fp8_f32 v253, v0, v177
	v_add_f32_e32 v219, v179, v219
	v_add_f32_e32 v219, v254, v219
	v_cvt_pk_fp8_f32 v253, v179, v254 op_sel:[0,0,1]
	ds_read_b128 v[122:125], v185 offset:8192
	ds_read_b128 v[126:129], v186 offset:8192
	ds_read_b128 v[114:117], v185 offset:10240
	ds_read_b128 v[118:121], v186 offset:10240
	ds_read_b128 v[106:109], v185 offset:12288
	ds_read_b128 v[110:113], v186 offset:12288
	ds_read_b128 v[98:101], v185 offset:14336
	ds_read_b128 v[102:105], v186 offset:14336
	s_waitcnt lgkmcnt(8)
	v_mfma_scale_f32_32x32x64_f8f6f4 v[66:81], v[222:229], v[130:137], v[66:81], v194, v193 op_sel_hi:[0,0,0]
	v_mov_b32_e32 v0, v219
	s_nop 1
	v_permlane32_swap_b32_e32 v219, v0
	v_add_f32_e32 v219, v219, v0
	v_fma_f32 v209, v209, v221, v219
	v_max_f32_e32 v177, v82, v83
	v_max3_f32 v177, v177, v84, v85
	v_max3_f32 v177, v177, v86, v87
	v_max3_f32 v177, v177, v88, v89
	v_max3_f32 v177, v177, v90, v91
	v_max3_f32 v177, v177, v92, v93
	v_max3_f32 v177, v177, v94, v95
	v_max3_f32 v177, v177, v96, v97
	s_waitcnt lgkmcnt(6)
	v_mfma_scale_f32_32x32x64_f8f6f4 v[50:65], v[246:253], v[122:129], v[50:65], v194, v194 op_sel_hi:[0,0,0]
	s_waitcnt lgkmcnt(4)
	v_mfma_scale_f32_32x32x64_f8f6f4 v[34:49], v[246:253], v[114:121], v[34:49], v194, v194 op_sel_hi:[0,0,0]
	s_waitcnt vmcnt(0)
	s_waitcnt lgkmcnt(0)
	s_barrier
	s_add_i32 m0, s98, 0x2000
	s_nop 0
	global_load_lds_dwordx4 v176, s[18:19]
	s_add_i32 m0, s98, 0x6000
	s_nop 0
	global_load_lds_dwordx4 v178, s[16:17]
	v_add_u32_e32 v176, 0x2000, v176
	v_add_u32_e32 v178, 0x20000, v178
	s_waitcnt lgkmcnt(2)
	v_mfma_scale_f32_32x32x64_f8f6f4 v[18:33], v[246:253], v[106:113], v[18:33], v194, v194 op_sel_hi:[0,0,0]
	s_waitcnt lgkmcnt(0)
	v_mfma_scale_f32_32x32x64_f8f6f4 v[2:17], v[246:253], v[98:105], v[2:17], v194, v194 op_sel_hi:[0,0,0]
	v_max_f32_e32 v0, v66, v67
	v_max3_f32 v0, v0, v68, v69
	v_max3_f32 v0, v0, v70, v71
	v_max3_f32 v0, v0, v72, v73
	v_max3_f32 v0, v0, v74, v75
	v_max3_f32 v0, v0, v76, v77
	v_max3_f32 v0, v0, v78, v79
	v_max3_f32 v0, v0, v80, v81
	v_max_f32_e32 v177, v177, v0
	v_mov_b32_e32 v0, v177
	v_mov_b32_e32 v218, 1.0
	s_nop 0
	v_permlane32_swap_b32_e32 v177, v0
	v_max_f32_e32 v177, v177, v0
	v_cmp_ge_f32_e32 vcc, s90, v177
	s_cmp_eq_u64 vcc, exec
	s_cbranch_scc0 .Lmla_s1_newmax
; __device__ __forceinline__ void finishSM9(f32x16& p0, f32x16& p1, float alpha, float& l_reg, v8i32& p8) {
; #pragma unroll
;   for (int r = 0; r < 16; ++r) { p0[r] = __builtin_amdgcn_exp2f(p0[r]); p1[r] = __builtin_amdgcn_exp2f(p1[r]); }
;   float ps = 0;
; #pragma unroll
;   for (int r = 0; r < 16; ++r) ps += p0[r];
; #pragma unroll
;   for (int r = 0; r < 16; ++r) ps += p1[r];
;   { auto rr = __builtin_amdgcn_permlane32_swap(__float_as_uint(ps), __float_as_uint(ps), false, false);
;     ps = __uint_as_float(rr[0]) + __uint_as_float(rr[1]); }
;   l_reg = l_reg * alpha + ps;
; #pragma unroll
;   for (int g = 0; g < 4; ++g) {
;     int w = __builtin_amdgcn_cvt_pk_fp8_f32(p0[4 * g], p0[4 * g + 1], 0, false); p8[g] = __builtin_amdgcn_cvt_pk_fp8_f32(p0[4 * g + 2], p0[4 * g + 3], w, true);
;     int u = __builtin_amdgcn_cvt_pk_fp8_f32(p1[4 * g], p1[4 * g + 1], 0, false); p8[4 + g] = __builtin_amdgcn_cvt_pk_fp8_f32(p1[4 * g + 2], p1[4 * g + 3], u, true); }
; }
; __device__ __forceinline__ void pv8(f32x16* o, const char* Vt, const v8i32 p8, int r32, int hi) {
;   const int sw = (r32 >> 2) & 3, a0 = r32 * 64 + (((hi * 2) ^ sw) << 4), a1 = r32 * 64 + (((hi * 2 + 1) ^ sw) << 4);
; #pragma unroll
;   for (int d0 = 0; d0 < 4; ++d0) {
;     const v8i32 vf = cat8(*reinterpret_cast<const v4i32*>(Vt + d0 * 2048 + a0), *reinterpret_cast<const v4i32*>(Vt + d0 * 2048 + a1));
;     o[d0] = __builtin_amdgcn_mfma_scale_f32_32x32x64_f8f6f4(p8, vf, o[d0], 0, 0, 0, 127, 0, 127); }
; }
; __device__ __forceinline__ void qkt9(f32x16& p0, f32x16& p1, const char* Kn, const char* Kr, const v8i32* qf, const float init, int r32, int hi) {
; #pragma unroll
;   for (int r = 0; r < 16; ++r) { p0[r] = init; p1[r] = init; }
; #pragma unroll
;   for (int s = 0; s < 2; ++s) { const int c0 = s * 4 + hi * 2;
;     const v8i32 a0 = cat8(*reinterpret_cast<const v4i32*>(Kn + KN8SW(r32, c0)), *reinterpret_cast<const v4i32*>(Kn + KN8SW(r32, c0 + 1)));
;     const v8i32 a1 = cat8(*reinterpret_cast<const v4i32*>(Kn + 4096 + KN8SW(r32, c0)), *reinterpret_cast<const v4i32*>(Kn + 4096 + KN8SW(r32, c0 + 1)));
;     p0 = __builtin_amdgcn_mfma_scale_f32_32x32x64_f8f6f4(a0, qf[s], p0, 0, 0, 0, 127, 0, 124);
;     p1 = __builtin_amdgcn_mfma_scale_f32_32x32x64_f8f6f4(a1, qf[s], p1, 0, 0, 0, 127, 0, 124); }
;   { const int c0 = hi * 2;
.Lmla_s1_cont:
	ds_read_b128 v[114:117], v215 offset:16384
	ds_read_b128 v[118:121], v216 offset:16384
	ds_read_b128 v[222:225], v215 offset:20480
	ds_read_b128 v[226:229], v216 offset:20480
	v_exp_f32_e32 v0, v82
	v_exp_f32_e32 v177, v83
	v_exp_f32_e32 v179, v84
	v_exp_f32_e32 v254, v85
	v_add_f32_e32 v219, v0, v177
	v_cvt_pk_fp8_f32 v246, v0, v177
	v_add_f32_e32 v219, v179, v219
	v_add_f32_e32 v219, v254, v219
	v_cvt_pk_fp8_f32 v246, v179, v254 op_sel:[0,0,1]
	s_waitcnt lgkmcnt(2)
	v_mfma_scale_f32_32x32x64_f8f6f4 v[114:129], v[114:121], v[146:153], v[230:245], v194, v193 op_sel_hi:[0,0,0]
	v_exp_f32_e32 v0, v86
	v_exp_f32_e32 v177, v87
	v_exp_f32_e32 v179, v88
	v_exp_f32_e32 v254, v89
	v_add_f32_e32 v219, v0, v219
	v_add_f32_e32 v219, v177, v219
	v_cvt_pk_fp8_f32 v247, v0, v177
	v_add_f32_e32 v219, v179, v219
	v_add_f32_e32 v219, v254, v219
	v_cvt_pk_fp8_f32 v247, v179, v254 op_sel:[0,0,1]
	ds_read_b128 v[82:85], v213 offset:16384
	ds_read_b128 v[86:89], v214 offset:16384
	s_waitcnt lgkmcnt(2)
	v_mfma_scale_f32_32x32x64_f8f6f4 v[98:113], v[222:229], v[146:153], v[230:245], v194, v193 op_sel_hi:[0,0,0]
	ds_read_b128 v[222:225], v213 offset:20480
	ds_read_b128 v[226:229], v214 offset:20480
	v_exp_f32_e32 v0, v90
	v_exp_f32_e32 v177, v91
	v_exp_f32_e32 v179, v92
	v_exp_f32_e32 v254, v93
	v_add_f32_e32 v219, v0, v219
	v_add_f32_e32 v219, v177, v219
	v_cvt_pk_fp8_f32 v248, v0, v177
	v_add_f32_e32 v219, v179, v219
	v_add_f32_e32 v219, v254, v219
	v_cvt_pk_fp8_f32 v248, v179, v254 op_sel:[0,0,1]
	v_exp_f32_e32 v0, v94
	v_exp_f32_e32 v177, v95
	v_exp_f32_e32 v179, v96
	v_exp_f32_e32 v254, v97
	v_add_f32_e32 v219, v0, v219
	v_add_f32_e32 v219, v177, v219
	v_cvt_pk_fp8_f32 v249, v0, v177
	v_add_f32_e32 v219, v179, v219
	v_add_f32_e32 v219, v254, v219
	v_cvt_pk_fp8_f32 v249, v179, v254 op_sel:[0,0,1]
	ds_read_b128 v[90:93], v185 offset:32768
	ds_read_b128 v[94:97], v186 offset:32768
	s_waitcnt lgkmcnt(4)
	v_mfma_scale_f32_32x32x64_f8f6f4 v[114:129], v[82:89], v[138:145], v[114:129], v194, v193 op_sel_hi:[0,0,0]
	v_exp_f32_e32 v0, v66
	v_exp_f32_e32 v177, v67
	v_exp_f32_e32 v179, v68
	v_exp_f32_e32 v254, v69
	v_add_f32_e32 v219, v0, v219
	v_add_f32_e32 v219, v177, v219
	v_cvt_pk_fp8_f32 v250, v0, v177
	v_add_f32_e32 v219, v179, v219
	v_add_f32_e32 v219, v254, v219
	v_cvt_pk_fp8_f32 v250, v179, v254 op_sel:[0,0,1]
	s_waitcnt lgkmcnt(2)
	v_mfma_scale_f32_32x32x64_f8f6f4 v[98:113], v[222:229], v[138:145], v[98:113], v194, v193 op_sel_hi:[0,0,0]
	ds_read_b128 v[222:225], v185 offset:34816
	ds_read_b128 v[226:229], v186 offset:34816
	v_exp_f32_e32 v0, v70
	v_exp_f32_e32 v177, v71
	v_exp_f32_e32 v179, v72
	v_exp_f32_e32 v254, v73
	v_add_f32_e32 v219, v0, v219
	v_add_f32_e32 v219, v177, v219
	v_cvt_pk_fp8_f32 v251, v0, v177
	v_add_f32_e32 v219, v179, v219
	v_add_f32_e32 v219, v254, v219
	v_cvt_pk_fp8_f32 v251, v179, v254 op_sel:[0,0,1]
	v_exp_f32_e32 v0, v74
	v_exp_f32_e32 v177, v75
	v_exp_f32_e32 v179, v76
	v_exp_f32_e32 v254, v77
	v_add_f32_e32 v219, v0, v219
	v_add_f32_e32 v219, v177, v219
	v_cvt_pk_fp8_f32 v252, v0, v177
	v_add_f32_e32 v219, v179, v219
	v_add_f32_e32 v219, v254, v219
	v_cvt_pk_fp8_f32 v252, v179, v254 op_sel:[0,0,1]
	s_waitcnt lgkmcnt(2)
	v_mfma_scale_f32_32x32x64_f8f6f4 v[114:129], v[90:97], v[130:137], v[114:129], v194, v193 op_sel_hi:[0,0,0]
	v_exp_f32_e32 v0, v78
	v_exp_f32_e32 v177, v79
	v_exp_f32_e32 v179, v80
	v_exp_f32_e32 v254, v81
	v_add_f32_e32 v219, v0, v219
	v_add_f32_e32 v219, v177, v219
	v_cvt_pk_fp8_f32 v253, v0, v177
	v_add_f32_e32 v219, v179, v219
	v_add_f32_e32 v219, v254, v219
	v_cvt_pk_fp8_f32 v253, v179, v254 op_sel:[0,0,1]
	ds_read_b128 v[90:93], v185 offset:43008
	ds_read_b128 v[94:97], v186 offset:43008
	ds_read_b128 v[82:85], v185 offset:45056
	ds_read_b128 v[86:89], v186 offset:45056
	ds_read_b128 v[74:77], v185 offset:47104
	ds_read_b128 v[78:81], v186 offset:47104
	ds_read_b128 v[66:69], v185 offset:49152
	ds_read_b128 v[70:73], v186 offset:49152
	s_waitcnt lgkmcnt(8)
	v_mfma_scale_f32_32x32x64_f8f6f4 v[98:113], v[222:229], v[130:137], v[98:113], v194, v193 op_sel_hi:[0,0,0]
	v_mov_b32_e32 v0, v219
	s_nop 1
	v_permlane32_swap_b32_e32 v219, v0
	v_add_f32_e32 v219, v219, v0
	v_fma_f32 v209, v209, v218, v219
	v_max_f32_e32 v177, v114, v115
	v_max3_f32 v177, v177, v116, v117
	v_max3_f32 v177, v177, v118, v119
	v_max3_f32 v177, v177, v120, v121
	v_max3_f32 v177, v177, v122, v123
	v_max3_f32 v177, v177, v124, v125
	v_max3_f32 v177, v177, v126, v127
	v_max3_f32 v177, v177, v128, v129
	s_waitcnt lgkmcnt(6)
	v_mfma_scale_f32_32x32x64_f8f6f4 v[50:65], v[246:253], v[90:97], v[50:65], v194, v194 op_sel_hi:[0,0,0]
	s_waitcnt lgkmcnt(4)
	v_mfma_scale_f32_32x32x64_f8f6f4 v[34:49], v[246:253], v[82:89], v[34:49], v194, v194 op_sel_hi:[0,0,0]
	s_waitcnt vmcnt(0)
	s_waitcnt lgkmcnt(0)
	s_barrier
	s_add_i32 m0, s98, 0xa800
	s_nop 0
	global_load_lds_dwordx4 v176, s[18:19]
	s_add_i32 m0, s98, 0xc800
	s_nop 0
	global_load_lds_dwordx4 v178, s[16:17]
	v_add_u32_e32 v176, 0x2000, v176
	v_add_u32_e32 v178, 0x20000, v178
	s_waitcnt lgkmcnt(2)
	v_mfma_scale_f32_32x32x64_f8f6f4 v[18:33], v[246:253], v[74:81], v[18:33], v194, v194 op_sel_hi:[0,0,0]
	s_waitcnt lgkmcnt(0)
	v_mfma_scale_f32_32x32x64_f8f6f4 v[2:17], v[246:253], v[66:73], v[2:17], v194, v194 op_sel_hi:[0,0,0]
	v_max_f32_e32 v0, v98, v99
	v_max3_f32 v0, v0, v100, v101
	v_max3_f32 v0, v0, v102, v103
	v_max3_f32 v0, v0, v104, v105
	v_max3_f32 v0, v0, v106, v107
	v_max3_f32 v0, v0, v108, v109
	v_max3_f32 v0, v0, v110, v111
	v_max3_f32 v0, v0, v112, v113
	v_max_f32_e32 v177, v177, v0
	v_mov_b32_e32 v0, v177
	v_mov_b32_e32 v221, 1.0
	s_nop 0
	v_permlane32_swap_b32_e32 v177, v0
	v_max_f32_e32 v177, v177, v0
	v_cmp_ge_f32_e32 vcc, s90, v177
	s_cmp_eq_u64 vcc, exec
	s_cbranch_scc0 .Lmla_s2_newmax
; __device__ __forceinline__ void finishSM9(f32x16& p0, f32x16& p1, float alpha, float& l_reg, v8i32& p8) {
; #pragma unroll
;   for (int r = 0; r < 16; ++r) { p0[r] = __builtin_amdgcn_exp2f(p0[r]); p1[r] = __builtin_amdgcn_exp2f(p1[r]); }
;   float ps = 0;
; #pragma unroll
;   for (int r = 0; r < 16; ++r) ps += p0[r];
; #pragma unroll
;   for (int r = 0; r < 16; ++r) ps += p1[r];
;   { auto rr = __builtin_amdgcn_permlane32_swap(__float_as_uint(ps), __float_as_uint(ps), false, false);
;     ps = __uint_as_float(rr[0]) + __uint_as_float(rr[1]); }
;   l_reg = l_reg * alpha + ps;
; #pragma unroll
;   for (int g = 0; g < 4; ++g) {
;     int w = __builtin_amdgcn_cvt_pk_fp8_f32(p0[4 * g], p0[4 * g + 1], 0, false); p8[g] = __builtin_amdgcn_cvt_pk_fp8_f32(p0[4 * g + 2], p0[4 * g + 3], w, true);
;     int u = __builtin_amdgcn_cvt_pk_fp8_f32(p1[4 * g], p1[4 * g + 1], 0, false); p8[4 + g] = __builtin_amdgcn_cvt_pk_fp8_f32(p1[4 * g + 2], p1[4 * g + 3], u, true); }
; }
; __device__ __forceinline__ void pv8(f32x16* o, const char* Vt, const v8i32 p8, int r32, int hi) {
;   const int sw = (r32 >> 2) & 3, a0 = r32 * 64 + (((hi * 2) ^ sw) << 4), a1 = r32 * 64 + (((hi * 2 + 1) ^ sw) << 4);
; #pragma unroll
;   for (int d0 = 0; d0 < 4; ++d0) {
;     const v8i32 vf = cat8(*reinterpret_cast<const v4i32*>(Vt + d0 * 2048 + a0), *reinterpret_cast<const v4i32*>(Vt + d0 * 2048 + a1));
;     o[d0] = __builtin_amdgcn_mfma_scale_f32_32x32x64_f8f6f4(p8, vf, o[d0], 0, 0, 0, 127, 0, 127); }
; }
; __device__ __forceinline__ void qkt9(f32x16& p0, f32x16& p1, const char* Kn, const char* Kr, const v8i32* qf, const float init, int r32, int hi) {
; #pragma unroll
;   for (int r = 0; r < 16; ++r) { p0[r] = init; p1[r] = init; }
; #pragma unroll
;   for (int s = 0; s < 2; ++s) { const int c0 = s * 4 + hi * 2;
;     const v8i32 a0 = cat8(*reinterpret_cast<const v4i32*>(Kn + KN8SW(r32, c0)), *reinterpret_cast<const v4i32*>(Kn + KN8SW(r32, c0 + 1)));
;     const v8i32 a1 = cat8(*reinterpret_cast<const v4i32*>(Kn + 4096 + KN8SW(r32, c0)), *reinterpret_cast<const v4i32*>(Kn + 4096 + KN8SW(r32, c0 + 1)));
;     p0 = __builtin_amdgcn_mfma_scale_f32_32x32x64_f8f6f4(a0, qf[s], p0, 0, 0, 0, 127, 0, 124);
;     p1 = __builtin_amdgcn_mfma_scale_f32_32x32x64_f8f6f4(a1, qf[s], p1, 0, 0, 0, 127, 0, 124); }
;   { const int c0 = hi * 2;
.Lmla_s2_cont:
	ds_read_b128 v[82:85], v215 offset:24576
	ds_read_b128 v[86:89], v216 offset:24576
	ds_read_b128 v[222:225], v215 offset:28672
	ds_read_b128 v[226:229], v216 offset:28672
	v_exp_f32_e32 v0, v114
	v_exp_f32_e32 v177, v115
	v_exp_f32_e32 v179, v116
	v_exp_f32_e32 v254, v117
	v_add_f32_e32 v219, v0, v177
	v_cvt_pk_fp8_f32 v246, v0, v177
	v_add_f32_e32 v219, v179, v219
	v_add_f32_e32 v219, v254, v219
	v_cvt_pk_fp8_f32 v246, v179, v254 op_sel:[0,0,1]
	s_waitcnt lgkmcnt(2)
	v_mfma_scale_f32_32x32x64_f8f6f4 v[82:97], v[82:89], v[146:153], v[230:245], v194, v193 op_sel_hi:[0,0,0]
	v_exp_f32_e32 v0, v118
	v_exp_f32_e32 v177, v119
	v_exp_f32_e32 v179, v120
	v_exp_f32_e32 v254, v121
	v_add_f32_e32 v219, v0, v219
	v_add_f32_e32 v219, v177, v219
	v_cvt_pk_fp8_f32 v247, v0, v177
	v_add_f32_e32 v219, v179, v219
	v_add_f32_e32 v219, v254, v219
	v_cvt_pk_fp8_f32 v247, v179, v254 op_sel:[0,0,1]
	ds_read_b128 v[114:117], v213 offset:24576
	ds_read_b128 v[118:121], v214 offset:24576
	s_waitcnt lgkmcnt(2)
	v_mfma_scale_f32_32x32x64_f8f6f4 v[66:81], v[222:229], v[146:153], v[230:245], v194, v193 op_sel_hi:[0,0,0]
	ds_read_b128 v[222:225], v213 offset:28672
	ds_read_b128 v[226:229], v214 offset:28672
	v_exp_f32_e32 v0, v122
	v_exp_f32_e32 v177, v123
	v_exp_f32_e32 v179, v124
	v_exp_f32_e32 v254, v125
	v_add_f32_e32 v219, v0, v219
	v_add_f32_e32 v219, v177, v219
	v_cvt_pk_fp8_f32 v248, v0, v177
	v_add_f32_e32 v219, v179, v219
	v_add_f32_e32 v219, v254, v219
	v_cvt_pk_fp8_f32 v248, v179, v254 op_sel:[0,0,1]
	v_exp_f32_e32 v0, v126
	v_exp_f32_e32 v177, v127
	v_exp_f32_e32 v179, v128
	v_exp_f32_e32 v254, v129
	v_add_f32_e32 v219, v0, v219
	v_add_f32_e32 v219, v177, v219
	v_cvt_pk_fp8_f32 v249, v0, v177
	v_add_f32_e32 v219, v179, v219
	v_add_f32_e32 v219, v254, v219
	v_cvt_pk_fp8_f32 v249, v179, v254 op_sel:[0,0,1]
	ds_read_b128 v[122:125], v185 offset:36864
	ds_read_b128 v[126:129], v186 offset:36864
	s_waitcnt lgkmcnt(4)
	v_mfma_scale_f32_32x32x64_f8f6f4 v[82:97], v[114:121], v[138:145], v[82:97], v194, v193 op_sel_hi:[0,0,0]
	v_exp_f32_e32 v0, v98
	v_exp_f32_e32 v177, v99
	v_exp_f32_e32 v179, v100
	v_exp_f32_e32 v254, v101
	v_add_f32_e32 v219, v0, v219
	v_add_f32_e32 v219, v177, v219
	v_cvt_pk_fp8_f32 v250, v0, v177
	v_add_f32_e32 v219, v179, v219
	v_add_f32_e32 v219, v254, v219
	v_cvt_pk_fp8_f32 v250, v179, v254 op_sel:[0,0,1]
	s_waitcnt lgkmcnt(2)
	v_mfma_scale_f32_32x32x64_f8f6f4 v[66:81], v[222:229], v[138:145], v[66:81], v194, v193 op_sel_hi:[0,0,0]
	ds_read_b128 v[222:225], v185 offset:38912
	ds_read_b128 v[226:229], v186 offset:38912
	v_exp_f32_e32 v0, v102
	v_exp_f32_e32 v177, v103
	v_exp_f32_e32 v179, v104
	v_exp_f32_e32 v254, v105
	v_add_f32_e32 v219, v0, v219
	v_add_f32_e32 v219, v177, v219
	v_cvt_pk_fp8_f32 v251, v0, v177
	v_add_f32_e32 v219, v179, v219
	v_add_f32_e32 v219, v254, v219
	v_cvt_pk_fp8_f32 v251, v179, v254 op_sel:[0,0,1]
	v_exp_f32_e32 v0, v106
	v_exp_f32_e32 v177, v107
	v_exp_f32_e32 v179, v108
	v_exp_f32_e32 v254, v109
	v_add_f32_e32 v219, v0, v219
	v_add_f32_e32 v219, v177, v219
	v_cvt_pk_fp8_f32 v252, v0, v177
	v_add_f32_e32 v219, v179, v219
	v_add_f32_e32 v219, v254, v219
	v_cvt_pk_fp8_f32 v252, v179, v254 op_sel:[0,0,1]
	s_waitcnt lgkmcnt(2)
	v_mfma_scale_f32_32x32x64_f8f6f4 v[82:97], v[122:129], v[130:137], v[82:97], v194, v193 op_sel_hi:[0,0,0]
	v_exp_f32_e32 v0, v110
	v_exp_f32_e32 v177, v111
	v_exp_f32_e32 v179, v112
	v_exp_f32_e32 v254, v113
	v_add_f32_e32 v219, v0, v219
	v_add_f32_e32 v219, v177, v219
	v_cvt_pk_fp8_f32 v253, v0, v177
	v_add_f32_e32 v219, v179, v219
	v_add_f32_e32 v219, v254, v219
	v_cvt_pk_fp8_f32 v253, v179, v254 op_sel:[0,0,1]
	ds_read_b128 v[122:125], v185 offset:0
	ds_read_b128 v[126:129], v186 offset:0
	ds_read_b128 v[114:117], v185 offset:2048
	ds_read_b128 v[118:121], v186 offset:2048
	ds_read_b128 v[106:109], v185 offset:4096
	ds_read_b128 v[110:113], v186 offset:4096
	ds_read_b128 v[98:101], v185 offset:6144
	ds_read_b128 v[102:105], v186 offset:6144
	s_waitcnt lgkmcnt(8)
	v_mfma_scale_f32_32x32x64_f8f6f4 v[66:81], v[222:229], v[130:137], v[66:81], v194, v193 op_sel_hi:[0,0,0]
	v_mov_b32_e32 v0, v219
	s_nop 1
	v_permlane32_swap_b32_e32 v219, v0
	v_add_f32_e32 v219, v219, v0
	v_fma_f32 v209, v209, v221, v219
	v_max_f32_e32 v177, v82, v83
	v_max3_f32 v177, v177, v84, v85
	v_max3_f32 v177, v177, v86, v87
	v_max3_f32 v177, v177, v88, v89
	v_max3_f32 v177, v177, v90, v91
	v_max3_f32 v177, v177, v92, v93
	v_max3_f32 v177, v177, v94, v95
	v_max3_f32 v177, v177, v96, v97
	s_waitcnt lgkmcnt(6)
	v_mfma_scale_f32_32x32x64_f8f6f4 v[50:65], v[246:253], v[122:129], v[50:65], v194, v194 op_sel_hi:[0,0,0]
	s_waitcnt lgkmcnt(4)
	v_mfma_scale_f32_32x32x64_f8f6f4 v[34:49], v[246:253], v[114:121], v[34:49], v194, v194 op_sel_hi:[0,0,0]
	s_waitcnt vmcnt(0)
	s_waitcnt lgkmcnt(0)
	s_barrier
	s_add_i32 m0, s98, 0x0
	s_nop 0
	global_load_lds_dwordx4 v176, s[18:19]
	s_add_i32 m0, s98, 0x4000
	s_nop 0
	global_load_lds_dwordx4 v178, s[16:17]
	v_add_u32_e32 v176, 0x2000, v176
	v_add_u32_e32 v178, 0x20000, v178
	s_waitcnt lgkmcnt(2)
	v_mfma_scale_f32_32x32x64_f8f6f4 v[18:33], v[246:253], v[106:113], v[18:33], v194, v194 op_sel_hi:[0,0,0]
	s_waitcnt lgkmcnt(0)
	v_mfma_scale_f32_32x32x64_f8f6f4 v[2:17], v[246:253], v[98:105], v[2:17], v194, v194 op_sel_hi:[0,0,0]
	v_max_f32_e32 v0, v66, v67
	v_max3_f32 v0, v0, v68, v69
	v_max3_f32 v0, v0, v70, v71
	v_max3_f32 v0, v0, v72, v73
	v_max3_f32 v0, v0, v74, v75
	v_max3_f32 v0, v0, v76, v77
	v_max3_f32 v0, v0, v78, v79
	v_max3_f32 v0, v0, v80, v81
	v_max_f32_e32 v177, v177, v0
	v_mov_b32_e32 v0, v177
	v_mov_b32_e32 v218, 1.0
	s_nop 0
	v_permlane32_swap_b32_e32 v177, v0
	v_max_f32_e32 v177, v177, v0
	v_cmp_ge_f32_e32 vcc, s90, v177
	s_cmp_eq_u64 vcc, exec
	s_cbranch_scc0 .Lmla_s3_newmax
; __device__ __forceinline__ void finishSM9(f32x16& p0, f32x16& p1, float alpha, float& l_reg, v8i32& p8) {
; #pragma unroll
;   for (int r = 0; r < 16; ++r) { p0[r] = __builtin_amdgcn_exp2f(p0[r]); p1[r] = __builtin_amdgcn_exp2f(p1[r]); }
;   float ps = 0;
; #pragma unroll
;   for (int r = 0; r < 16; ++r) ps += p0[r];
; #pragma unroll
;   for (int r = 0; r < 16; ++r) ps += p1[r];
;   { auto rr = __builtin_amdgcn_permlane32_swap(__float_as_uint(ps), __float_as_uint(ps), false, false);
;     ps = __uint_as_float(rr[0]) + __uint_as_float(rr[1]); }
;   l_reg = l_reg * alpha + ps;
; #pragma unroll
;   for (int g = 0; g < 4; ++g) {
;     int w = __builtin_amdgcn_cvt_pk_fp8_f32(p0[4 * g], p0[4 * g + 1], 0, false); p8[g] = __builtin_amdgcn_cvt_pk_fp8_f32(p0[4 * g + 2], p0[4 * g + 3], w, true);
;     int u = __builtin_amdgcn_cvt_pk_fp8_f32(p1[4 * g], p1[4 * g + 1], 0, false); p8[4 + g] = __builtin_amdgcn_cvt_pk_fp8_f32(p1[4 * g + 2], p1[4 * g + 3], u, true); }
; }
; __device__ __forceinline__ void pv8(f32x16* o, const char* Vt, const v8i32 p8, int r32, int hi) {
;   const int sw = (r32 >> 2) & 3, a0 = r32 * 64 + (((hi * 2) ^ sw) << 4), a1 = r32 * 64 + (((hi * 2 + 1) ^ sw) << 4);
; #pragma unroll
;   for (int d0 = 0; d0 < 4; ++d0) {
;     const v8i32 vf = cat8(*reinterpret_cast<const v4i32*>(Vt + d0 * 2048 + a0), *reinterpret_cast<const v4i32*>(Vt + d0 * 2048 + a1));
;     o[d0] = __builtin_amdgcn_mfma_scale_f32_32x32x64_f8f6f4(p8, vf, o[d0], 0, 0, 0, 127, 0, 127); }
; }
; __device__ __forceinline__ void qkt9(f32x16& p0, f32x16& p1, const char* Kn, const char* Kr, const v8i32* qf, const float init, int r32, int hi) {
; #pragma unroll
;   for (int r = 0; r < 16; ++r) { p0[r] = init; p1[r] = init; }
; #pragma unroll
;   for (int s = 0; s < 2; ++s) { const int c0 = s * 4 + hi * 2;
;     const v8i32 a0 = cat8(*reinterpret_cast<const v4i32*>(Kn + KN8SW(r32, c0)), *reinterpret_cast<const v4i32*>(Kn + KN8SW(r32, c0 + 1)));
;     const v8i32 a1 = cat8(*reinterpret_cast<const v4i32*>(Kn + 4096 + KN8SW(r32, c0)), *reinterpret_cast<const v4i32*>(Kn + 4096 + KN8SW(r32, c0 + 1)));
;     p0 = __builtin_amdgcn_mfma_scale_f32_32x32x64_f8f6f4(a0, qf[s], p0, 0, 0, 0, 127, 0, 124);
;     p1 = __builtin_amdgcn_mfma_scale_f32_32x32x64_f8f6f4(a1, qf[s], p1, 0, 0, 0, 127, 0, 124); }
;   { const int c0 = hi * 2;
.Lmla_s3_cont:
	ds_read_b128 v[114:117], v215 offset:51200
	ds_read_b128 v[118:121], v216 offset:51200
	ds_read_b128 v[222:225], v215 offset:55296
	ds_read_b128 v[226:229], v216 offset:55296
	v_exp_f32_e32 v0, v82
	v_exp_f32_e32 v177, v83
	v_exp_f32_e32 v179, v84
	v_exp_f32_e32 v254, v85
	v_add_f32_e32 v219, v0, v177
	v_cvt_pk_fp8_f32 v246, v0, v177
	v_add_f32_e32 v219, v179, v219
	v_add_f32_e32 v219, v254, v219
	v_cvt_pk_fp8_f32 v246, v179, v254 op_sel:[0,0,1]
	s_waitcnt lgkmcnt(2)
	v_mfma_scale_f32_32x32x64_f8f6f4 v[114:129], v[114:121], v[146:153], v[230:245], v194, v193 op_sel_hi:[0,0,0]
	v_exp_f32_e32 v0, v86
	v_exp_f32_e32 v177, v87
	v_exp_f32_e32 v179, v88
	v_exp_f32_e32 v254, v89
	v_add_f32_e32 v219, v0, v219
	v_add_f32_e32 v219, v177, v219
	v_cvt_pk_fp8_f32 v247, v0, v177
	v_add_f32_e32 v219, v179, v219
	v_add_f32_e32 v219, v254, v219
	v_cvt_pk_fp8_f32 v247, v179, v254 op_sel:[0,0,1]
	ds_read_b128 v[82:85], v213 offset:51200
	ds_read_b128 v[86:89], v214 offset:51200
	s_waitcnt lgkmcnt(2)
	v_mfma_scale_f32_32x32x64_f8f6f4 v[98:113], v[222:229], v[146:153], v[230:245], v194, v193 op_sel_hi:[0,0,0]
	ds_read_b128 v[222:225], v213 offset:55296
	ds_read_b128 v[226:229], v214 offset:55296
	v_exp_f32_e32 v0, v90
	v_exp_f32_e32 v177, v91
	v_exp_f32_e32 v179, v92
	v_exp_f32_e32 v254, v93
	v_add_f32_e32 v219, v0, v219
	v_add_f32_e32 v219, v177, v219
	v_cvt_pk_fp8_f32 v248, v0, v177
	v_add_f32_e32 v219, v179, v219
	v_add_f32_e32 v219, v254, v219
	v_cvt_pk_fp8_f32 v248, v179, v254 op_sel:[0,0,1]
	v_exp_f32_e32 v0, v94
	v_exp_f32_e32 v177, v95
	v_exp_f32_e32 v179, v96
	v_exp_f32_e32 v254, v97
	v_add_f32_e32 v219, v0, v219
	v_add_f32_e32 v219, v177, v219
	v_cvt_pk_fp8_f32 v249, v0, v177
	v_add_f32_e32 v219, v179, v219
	v_add_f32_e32 v219, v254, v219
	v_cvt_pk_fp8_f32 v249, v179, v254 op_sel:[0,0,1]
	ds_read_b128 v[90:93], v185 offset:59392
	ds_read_b128 v[94:97], v186 offset:59392
	s_waitcnt lgkmcnt(4)
	v_mfma_scale_f32_32x32x64_f8f6f4 v[114:129], v[82:89], v[138:145], v[114:129], v194, v193 op_sel_hi:[0,0,0]
	v_exp_f32_e32 v0, v66
	v_exp_f32_e32 v177, v67
	v_exp_f32_e32 v179, v68
	v_exp_f32_e32 v254, v69
	v_add_f32_e32 v219, v0, v219
	v_add_f32_e32 v219, v177, v219
	v_cvt_pk_fp8_f32 v250, v0, v177
	v_add_f32_e32 v219, v179, v219
	v_add_f32_e32 v219, v254, v219
	v_cvt_pk_fp8_f32 v250, v179, v254 op_sel:[0,0,1]
	s_waitcnt lgkmcnt(2)
	v_mfma_scale_f32_32x32x64_f8f6f4 v[98:113], v[222:229], v[138:145], v[98:113], v194, v193 op_sel_hi:[0,0,0]
	ds_read_b128 v[222:225], v185 offset:61440
	ds_read_b128 v[226:229], v186 offset:61440
	v_exp_f32_e32 v0, v70
	v_exp_f32_e32 v177, v71
	v_exp_f32_e32 v179, v72
	v_exp_f32_e32 v254, v73
	v_add_f32_e32 v219, v0, v219
	v_add_f32_e32 v219, v177, v219
	v_cvt_pk_fp8_f32 v251, v0, v177
	v_add_f32_e32 v219, v179, v219
	v_add_f32_e32 v219, v254, v219
	v_cvt_pk_fp8_f32 v251, v179, v254 op_sel:[0,0,1]
	v_exp_f32_e32 v0, v74
	v_exp_f32_e32 v177, v75
	v_exp_f32_e32 v179, v76
	v_exp_f32_e32 v254, v77
	v_add_f32_e32 v219, v0, v219
	v_add_f32_e32 v219, v177, v219
	v_cvt_pk_fp8_f32 v252, v0, v177
	v_add_f32_e32 v219, v179, v219
	v_add_f32_e32 v219, v254, v219
	v_cvt_pk_fp8_f32 v252, v179, v254 op_sel:[0,0,1]
	s_waitcnt lgkmcnt(2)
	v_mfma_scale_f32_32x32x64_f8f6f4 v[114:129], v[90:97], v[130:137], v[114:129], v194, v193 op_sel_hi:[0,0,0]
	v_exp_f32_e32 v0, v78
	v_exp_f32_e32 v177, v79
	v_exp_f32_e32 v179, v80
	v_exp_f32_e32 v254, v81
	v_add_f32_e32 v219, v0, v219
	v_add_f32_e32 v219, v177, v219
	v_cvt_pk_fp8_f32 v253, v0, v177
	v_add_f32_e32 v219, v179, v219
	v_add_f32_e32 v219, v254, v219
	v_cvt_pk_fp8_f32 v253, v179, v254 op_sel:[0,0,1]
	ds_read_b128 v[90:93], v185 offset:8192
	ds_read_b128 v[94:97], v186 offset:8192
	ds_read_b128 v[82:85], v185 offset:10240
	ds_read_b128 v[86:89], v186 offset:10240
	ds_read_b128 v[74:77], v185 offset:12288
	ds_read_b128 v[78:81], v186 offset:12288
	ds_read_b128 v[66:69], v185 offset:14336
	ds_read_b128 v[70:73], v186 offset:14336
	s_waitcnt lgkmcnt(8)
	v_mfma_scale_f32_32x32x64_f8f6f4 v[98:113], v[222:229], v[130:137], v[98:113], v194, v193 op_sel_hi:[0,0,0]
	v_mov_b32_e32 v0, v219
	s_nop 1
	v_permlane32_swap_b32_e32 v219, v0
	v_add_f32_e32 v219, v219, v0
	v_fma_f32 v209, v209, v218, v219
	v_max_f32_e32 v177, v114, v115
	v_max3_f32 v177, v177, v116, v117
	v_max3_f32 v177, v177, v118, v119
	v_max3_f32 v177, v177, v120, v121
	v_max3_f32 v177, v177, v122, v123
	v_max3_f32 v177, v177, v124, v125
	v_max3_f32 v177, v177, v126, v127
	v_max3_f32 v177, v177, v128, v129
	s_waitcnt lgkmcnt(6)
	v_mfma_scale_f32_32x32x64_f8f6f4 v[50:65], v[246:253], v[90:97], v[50:65], v194, v194 op_sel_hi:[0,0,0]
	s_waitcnt lgkmcnt(4)
	v_mfma_scale_f32_32x32x64_f8f6f4 v[34:49], v[246:253], v[82:89], v[34:49], v194, v194 op_sel_hi:[0,0,0]
	s_waitcnt vmcnt(0)
	s_waitcnt lgkmcnt(0)
	s_barrier
	s_add_i32 m0, s98, 0x2000
	s_nop 0
	global_load_lds_dwordx4 v176, s[18:19]
	s_add_i32 m0, s98, 0x6000
	s_nop 0
	global_load_lds_dwordx4 v178, s[16:17]
	v_add_u32_e32 v176, 0x2000, v176
	v_add_u32_e32 v178, 0x20000, v178
	s_waitcnt lgkmcnt(2)
	v_mfma_scale_f32_32x32x64_f8f6f4 v[18:33], v[246:253], v[74:81], v[18:33], v194, v194 op_sel_hi:[0,0,0]
	s_waitcnt lgkmcnt(0)
	v_mfma_scale_f32_32x32x64_f8f6f4 v[2:17], v[246:253], v[66:73], v[2:17], v194, v194 op_sel_hi:[0,0,0]
	v_max_f32_e32 v0, v98, v99
	v_max3_f32 v0, v0, v100, v101
	v_max3_f32 v0, v0, v102, v103
	v_max3_f32 v0, v0, v104, v105
	v_max3_f32 v0, v0, v106, v107
	v_max3_f32 v0, v0, v108, v109
	v_max3_f32 v0, v0, v110, v111
	v_max3_f32 v0, v0, v112, v113
	v_max_f32_e32 v177, v177, v0
	v_mov_b32_e32 v0, v177
	v_mov_b32_e32 v221, 1.0
	s_nop 0
	v_permlane32_swap_b32_e32 v177, v0
	v_max_f32_e32 v177, v177, v0
	v_cmp_ge_f32_e32 vcc, s90, v177
	s_cmp_eq_u64 vcc, exec
	s_cbranch_scc0 .Lmla_s4_newmax
; __device__ __forceinline__ void finishSM9(f32x16& p0, f32x16& p1, float alpha, float& l_reg, v8i32& p8) {
; #pragma unroll
;   for (int r = 0; r < 16; ++r) { p0[r] = __builtin_amdgcn_exp2f(p0[r]); p1[r] = __builtin_amdgcn_exp2f(p1[r]); }
;   float ps = 0;
; #pragma unroll
;   for (int r = 0; r < 16; ++r) ps += p0[r];
; #pragma unroll
;   for (int r = 0; r < 16; ++r) ps += p1[r];
;   { auto rr = __builtin_amdgcn_permlane32_swap(__float_as_uint(ps), __float_as_uint(ps), false, false);
;     ps = __uint_as_float(rr[0]) + __uint_as_float(rr[1]); }
;   l_reg = l_reg * alpha + ps;
; #pragma unroll
;   for (int g = 0; g < 4; ++g) {
;     int w = __builtin_amdgcn_cvt_pk_fp8_f32(p0[4 * g], p0[4 * g + 1], 0, false); p8[g] = __builtin_amdgcn_cvt_pk_fp8_f32(p0[4 * g + 2], p0[4 * g + 3], w, true);
;     int u = __builtin_amdgcn_cvt_pk_fp8_f32(p1[4 * g], p1[4 * g + 1], 0, false); p8[4 + g] = __builtin_amdgcn_cvt_pk_fp8_f32(p1[4 * g + 2], p1[4 * g + 3], u, true); }
; }
; __device__ __forceinline__ void pv8(f32x16* o, const char* Vt, const v8i32 p8, int r32, int hi) {
;   const int sw = (r32 >> 2) & 3, a0 = r32 * 64 + (((hi * 2) ^ sw) << 4), a1 = r32 * 64 + (((hi * 2 + 1) ^ sw) << 4);
; #pragma unroll
;   for (int d0 = 0; d0 < 4; ++d0) {
;     const v8i32 vf = cat8(*reinterpret_cast<const v4i32*>(Vt + d0 * 2048 + a0), *reinterpret_cast<const v4i32*>(Vt + d0 * 2048 + a1));
;     o[d0] = __builtin_amdgcn_mfma_scale_f32_32x32x64_f8f6f4(p8, vf, o[d0], 0, 0, 0, 127, 0, 127); }
; }
; __device__ __forceinline__ void qkt9(f32x16& p0, f32x16& p1, const char* Kn, const char* Kr, const v8i32* qf, const float init, int r32, int hi) {
; #pragma unroll
;   for (int r = 0; r < 16; ++r) { p0[r] = init; p1[r] = init; }
; #pragma unroll
;   for (int s = 0; s < 2; ++s) { const int c0 = s * 4 + hi * 2;
;     const v8i32 a0 = cat8(*reinterpret_cast<const v4i32*>(Kn + KN8SW(r32, c0)), *reinterpret_cast<const v4i32*>(Kn + KN8SW(r32, c0 + 1)));
;     const v8i32 a1 = cat8(*reinterpret_cast<const v4i32*>(Kn + 4096 + KN8SW(r32, c0)), *reinterpret_cast<const v4i32*>(Kn + 4096 + KN8SW(r32, c0 + 1)));
;     p0 = __builtin_amdgcn_mfma_scale_f32_32x32x64_f8f6f4(a0, qf[s], p0, 0, 0, 0, 127, 0, 124);
;     p1 = __builtin_amdgcn_mfma_scale_f32_32x32x64_f8f6f4(a1, qf[s], p1, 0, 0, 0, 127, 0, 124); }
;   { const int c0 = hi * 2;
.Lmla_s4_cont:
	ds_read_b128 v[82:85], v215 offset:16384
	ds_read_b128 v[86:89], v216 offset:16384
	ds_read_b128 v[222:225], v215 offset:20480
	ds_read_b128 v[226:229], v216 offset:20480
	v_exp_f32_e32 v0, v114
	v_exp_f32_e32 v177, v115
	v_exp_f32_e32 v179, v116
	v_exp_f32_e32 v254, v117
	v_add_f32_e32 v219, v0, v177
	v_cvt_pk_fp8_f32 v246, v0, v177
	v_add_f32_e32 v219, v179, v219
	v_add_f32_e32 v219, v254, v219
	v_cvt_pk_fp8_f32 v246, v179, v254 op_sel:[0,0,1]
	s_waitcnt lgkmcnt(2)
	v_mfma_scale_f32_32x32x64_f8f6f4 v[82:97], v[82:89], v[146:153], v[230:245], v194, v193 op_sel_hi:[0,0,0]
	v_exp_f32_e32 v0, v118
	v_exp_f32_e32 v177, v119
	v_exp_f32_e32 v179, v120
	v_exp_f32_e32 v254, v121
	v_add_f32_e32 v219, v0, v219
	v_add_f32_e32 v219, v177, v219
	v_cvt_pk_fp8_f32 v247, v0, v177
	v_add_f32_e32 v219, v179, v219
	v_add_f32_e32 v219, v254, v219
	v_cvt_pk_fp8_f32 v247, v179, v254 op_sel:[0,0,1]
	ds_read_b128 v[114:117], v213 offset:16384
	ds_read_b128 v[118:121], v214 offset:16384
	s_waitcnt lgkmcnt(2)
	v_mfma_scale_f32_32x32x64_f8f6f4 v[66:81], v[222:229], v[146:153], v[230:245], v194, v193 op_sel_hi:[0,0,0]
	ds_read_b128 v[222:225], v213 offset:20480
	ds_read_b128 v[226:229], v214 offset:20480
	v_exp_f32_e32 v0, v122
	v_exp_f32_e32 v177, v123
	v_exp_f32_e32 v179, v124
	v_exp_f32_e32 v254, v125
	v_add_f32_e32 v219, v0, v219
	v_add_f32_e32 v219, v177, v219
	v_cvt_pk_fp8_f32 v248, v0, v177
	v_add_f32_e32 v219, v179, v219
	v_add_f32_e32 v219, v254, v219
	v_cvt_pk_fp8_f32 v248, v179, v254 op_sel:[0,0,1]
	v_exp_f32_e32 v0, v126
	v_exp_f32_e32 v177, v127
	v_exp_f32_e32 v179, v128
	v_exp_f32_e32 v254, v129
	v_add_f32_e32 v219, v0, v219
	v_add_f32_e32 v219, v177, v219
	v_cvt_pk_fp8_f32 v249, v0, v177
	v_add_f32_e32 v219, v179, v219
	v_add_f32_e32 v219, v254, v219
	v_cvt_pk_fp8_f32 v249, v179, v254 op_sel:[0,0,1]
	ds_read_b128 v[122:125], v185 offset:32768
	ds_read_b128 v[126:129], v186 offset:32768
	s_waitcnt lgkmcnt(4)
	v_mfma_scale_f32_32x32x64_f8f6f4 v[82:97], v[114:121], v[138:145], v[82:97], v194, v193 op_sel_hi:[0,0,0]
	v_exp_f32_e32 v0, v98
	v_exp_f32_e32 v177, v99
	v_exp_f32_e32 v179, v100
	v_exp_f32_e32 v254, v101
	v_add_f32_e32 v219, v0, v219
	v_add_f32_e32 v219, v177, v219
	v_cvt_pk_fp8_f32 v250, v0, v177
	v_add_f32_e32 v219, v179, v219
	v_add_f32_e32 v219, v254, v219
	v_cvt_pk_fp8_f32 v250, v179, v254 op_sel:[0,0,1]
	s_waitcnt lgkmcnt(2)
	v_mfma_scale_f32_32x32x64_f8f6f4 v[66:81], v[222:229], v[138:145], v[66:81], v194, v193 op_sel_hi:[0,0,0]
	ds_read_b128 v[222:225], v185 offset:34816
	ds_read_b128 v[226:229], v186 offset:34816
	v_exp_f32_e32 v0, v102
	v_exp_f32_e32 v177, v103
	v_exp_f32_e32 v179, v104
	v_exp_f32_e32 v254, v105
	v_add_f32_e32 v219, v0, v219
	v_add_f32_e32 v219, v177, v219
	v_cvt_pk_fp8_f32 v251, v0, v177
	v_add_f32_e32 v219, v179, v219
	v_add_f32_e32 v219, v254, v219
	v_cvt_pk_fp8_f32 v251, v179, v254 op_sel:[0,0,1]
	v_exp_f32_e32 v0, v106
	v_exp_f32_e32 v177, v107
	v_exp_f32_e32 v179, v108
	v_exp_f32_e32 v254, v109
	v_add_f32_e32 v219, v0, v219
	v_add_f32_e32 v219, v177, v219
	v_cvt_pk_fp8_f32 v252, v0, v177
	v_add_f32_e32 v219, v179, v219
	v_add_f32_e32 v219, v254, v219
	v_cvt_pk_fp8_f32 v252, v179, v254 op_sel:[0,0,1]
	s_waitcnt lgkmcnt(2)
	v_mfma_scale_f32_32x32x64_f8f6f4 v[82:97], v[122:129], v[130:137], v[82:97], v194, v193 op_sel_hi:[0,0,0]
	v_exp_f32_e32 v0, v110
	v_exp_f32_e32 v177, v111
	v_exp_f32_e32 v179, v112
	v_exp_f32_e32 v254, v113
	v_add_f32_e32 v219, v0, v219
	v_add_f32_e32 v219, v177, v219
	v_cvt_pk_fp8_f32 v253, v0, v177
	v_add_f32_e32 v219, v179, v219
	v_add_f32_e32 v219, v254, v219
	v_cvt_pk_fp8_f32 v253, v179, v254 op_sel:[0,0,1]
	ds_read_b128 v[122:125], v185 offset:43008
	ds_read_b128 v[126:129], v186 offset:43008
	ds_read_b128 v[114:117], v185 offset:45056
	ds_read_b128 v[118:121], v186 offset:45056
	ds_read_b128 v[106:109], v185 offset:47104
	ds_read_b128 v[110:113], v186 offset:47104
	ds_read_b128 v[98:101], v185 offset:49152
	ds_read_b128 v[102:105], v186 offset:49152
	s_waitcnt lgkmcnt(8)
	v_mfma_scale_f32_32x32x64_f8f6f4 v[66:81], v[222:229], v[130:137], v[66:81], v194, v193 op_sel_hi:[0,0,0]
	v_mov_b32_e32 v0, v219
	s_nop 1
	v_permlane32_swap_b32_e32 v219, v0
	v_add_f32_e32 v219, v219, v0
	v_fma_f32 v209, v209, v221, v219
	v_max_f32_e32 v177, v82, v83
	v_max3_f32 v177, v177, v84, v85
	v_max3_f32 v177, v177, v86, v87
	v_max3_f32 v177, v177, v88, v89
	v_max3_f32 v177, v177, v90, v91
	v_max3_f32 v177, v177, v92, v93
	v_max3_f32 v177, v177, v94, v95
	v_max3_f32 v177, v177, v96, v97
	s_waitcnt lgkmcnt(6)
	v_mfma_scale_f32_32x32x64_f8f6f4 v[50:65], v[246:253], v[122:129], v[50:65], v194, v194 op_sel_hi:[0,0,0]
	s_waitcnt lgkmcnt(4)
	v_mfma_scale_f32_32x32x64_f8f6f4 v[34:49], v[246:253], v[114:121], v[34:49], v194, v194 op_sel_hi:[0,0,0]
	s_waitcnt vmcnt(0)
	s_waitcnt lgkmcnt(0)
	s_barrier
	s_add_i32 m0, s98, 0xa800
	s_nop 0
	global_load_lds_dwordx4 v176, s[18:19]
	s_add_i32 m0, s98, 0xc800
	s_nop 0
	global_load_lds_dwordx4 v178, s[16:17]
	v_add_u32_e32 v176, 0x2000, v176
	v_add_u32_e32 v178, 0x20000, v178
	s_waitcnt lgkmcnt(2)
	v_mfma_scale_f32_32x32x64_f8f6f4 v[18:33], v[246:253], v[106:113], v[18:33], v194, v194 op_sel_hi:[0,0,0]
	s_waitcnt lgkmcnt(0)
	v_mfma_scale_f32_32x32x64_f8f6f4 v[2:17], v[246:253], v[98:105], v[2:17], v194, v194 op_sel_hi:[0,0,0]
	v_max_f32_e32 v0, v66, v67
	v_max3_f32 v0, v0, v68, v69
	v_max3_f32 v0, v0, v70, v71
	v_max3_f32 v0, v0, v72, v73
	v_max3_f32 v0, v0, v74, v75
	v_max3_f32 v0, v0, v76, v77
	v_max3_f32 v0, v0, v78, v79
	v_max3_f32 v0, v0, v80, v81
	v_max_f32_e32 v177, v177, v0
	v_mov_b32_e32 v0, v177
	v_mov_b32_e32 v218, 1.0
	s_nop 0
	v_permlane32_swap_b32_e32 v177, v0
	v_max_f32_e32 v177, v177, v0
	v_cmp_ge_f32_e32 vcc, s90, v177
	s_cmp_eq_u64 vcc, exec
	s_cbranch_scc0 .Lmla_s5_newmax
; __device__ __forceinline__ void finishSM9(f32x16& p0, f32x16& p1, float alpha, float& l_reg, v8i32& p8) {
; #pragma unroll
;   for (int r = 0; r < 16; ++r) { p0[r] = __builtin_amdgcn_exp2f(p0[r]); p1[r] = __builtin_amdgcn_exp2f(p1[r]); }
;   float ps = 0;
; #pragma unroll
;   for (int r = 0; r < 16; ++r) ps += p0[r];
; #pragma unroll
;   for (int r = 0; r < 16; ++r) ps += p1[r];
;   { auto rr = __builtin_amdgcn_permlane32_swap(__float_as_uint(ps), __float_as_uint(ps), false, false);
;     ps = __uint_as_float(rr[0]) + __uint_as_float(rr[1]); }
;   l_reg = l_reg * alpha + ps;
; #pragma unroll
;   for (int g = 0; g < 4; ++g) {
;     int w = __builtin_amdgcn_cvt_pk_fp8_f32(p0[4 * g], p0[4 * g + 1], 0, false); p8[g] = __builtin_amdgcn_cvt_pk_fp8_f32(p0[4 * g + 2], p0[4 * g + 3], w, true);
;     int u = __builtin_amdgcn_cvt_pk_fp8_f32(p1[4 * g], p1[4 * g + 1], 0, false); p8[4 + g] = __builtin_amdgcn_cvt_pk_fp8_f32(p1[4 * g + 2], p1[4 * g + 3], u, true); }
; }
; __device__ __forceinline__ void pv8(f32x16* o, const char* Vt, const v8i32 p8, int r32, int hi) {
;   const int sw = (r32 >> 2) & 3, a0 = r32 * 64 + (((hi * 2) ^ sw) << 4), a1 = r32 * 64 + (((hi * 2 + 1) ^ sw) << 4);
; #pragma unroll
;   for (int d0 = 0; d0 < 4; ++d0) {
;     const v8i32 vf = cat8(*reinterpret_cast<const v4i32*>(Vt + d0 * 2048 + a0), *reinterpret_cast<const v4i32*>(Vt + d0 * 2048 + a1));
;     o[d0] = __builtin_amdgcn_mfma_scale_f32_32x32x64_f8f6f4(p8, vf, o[d0], 0, 0, 0, 127, 0, 127); }
; }
; __device__ __forceinline__ void qkt9(f32x16& p0, f32x16& p1, const char* Kn, const char* Kr, const v8i32* qf, const float init, int r32, int hi) {
; #pragma unroll
;   for (int r = 0; r < 16; ++r) { p0[r] = init; p1[r] = init; }
; #pragma unroll
;   for (int s = 0; s < 2; ++s) { const int c0 = s * 4 + hi * 2;
;     const v8i32 a0 = cat8(*reinterpret_cast<const v4i32*>(Kn + KN8SW(r32, c0)), *reinterpret_cast<const v4i32*>(Kn + KN8SW(r32, c0 + 1)));
;     const v8i32 a1 = cat8(*reinterpret_cast<const v4i32*>(Kn + 4096 + KN8SW(r32, c0)), *reinterpret_cast<const v4i32*>(Kn + 4096 + KN8SW(r32, c0 + 1)));
;     p0 = __builtin_amdgcn_mfma_scale_f32_32x32x64_f8f6f4(a0, qf[s], p0, 0, 0, 0, 127, 0, 124);
;     p1 = __builtin_amdgcn_mfma_scale_f32_32x32x64_f8f6f4(a1, qf[s], p1, 0, 0, 0, 127, 0, 124); }
;   { const int c0 = hi * 2;
.Lmla_s5_cont:
	s_add_i32 s30, s30, 1
	s_cmpk_lt_u32 s30, 42
	s_cbranch_scc1 .Lmla_stag_loop
	ds_read_b128 v[114:117], v215 offset:24576
	ds_read_b128 v[118:121], v216 offset:24576
	ds_read_b128 v[222:225], v215 offset:28672
	ds_read_b128 v[226:229], v216 offset:28672
	v_exp_f32_e32 v0, v82
	v_exp_f32_e32 v177, v83
	v_exp_f32_e32 v179, v84
	v_exp_f32_e32 v254, v85
	v_add_f32_e32 v219, v0, v177
	v_cvt_pk_fp8_f32 v246, v0, v177
	v_add_f32_e32 v219, v179, v219
	v_add_f32_e32 v219, v254, v219
	v_cvt_pk_fp8_f32 v246, v179, v254 op_sel:[0,0,1]
	s_waitcnt lgkmcnt(2)
	v_mfma_scale_f32_32x32x64_f8f6f4 v[114:129], v[114:121], v[146:153], v[230:245], v194, v193 op_sel_hi:[0,0,0]
	v_exp_f32_e32 v0, v86
	v_exp_f32_e32 v177, v87
	v_exp_f32_e32 v179, v88
	v_exp_f32_e32 v254, v89
	v_add_f32_e32 v219, v0, v219
	v_add_f32_e32 v219, v177, v219
	v_cvt_pk_fp8_f32 v247, v0, v177
	v_add_f32_e32 v219, v179, v219
	v_add_f32_e32 v219, v254, v219
	v_cvt_pk_fp8_f32 v247, v179, v254 op_sel:[0,0,1]
	ds_read_b128 v[82:85], v213 offset:24576
	ds_read_b128 v[86:89], v214 offset:24576
	s_waitcnt lgkmcnt(2)
	v_mfma_scale_f32_32x32x64_f8f6f4 v[98:113], v[222:229], v[146:153], v[230:245], v194, v193 op_sel_hi:[0,0,0]
	ds_read_b128 v[222:225], v213 offset:28672
	ds_read_b128 v[226:229], v214 offset:28672
	v_exp_f32_e32 v0, v90
	v_exp_f32_e32 v177, v91
	v_exp_f32_e32 v179, v92
	v_exp_f32_e32 v254, v93
	v_add_f32_e32 v219, v0, v219
	v_add_f32_e32 v219, v177, v219
	v_cvt_pk_fp8_f32 v248, v0, v177
	v_add_f32_e32 v219, v179, v219
	v_add_f32_e32 v219, v254, v219
	v_cvt_pk_fp8_f32 v248, v179, v254 op_sel:[0,0,1]
	v_exp_f32_e32 v0, v94
	v_exp_f32_e32 v177, v95
	v_exp_f32_e32 v179, v96
	v_exp_f32_e32 v254, v97
	v_add_f32_e32 v219, v0, v219
	v_add_f32_e32 v219, v177, v219
	v_cvt_pk_fp8_f32 v249, v0, v177
	v_add_f32_e32 v219, v179, v219
	v_add_f32_e32 v219, v254, v219
	v_cvt_pk_fp8_f32 v249, v179, v254 op_sel:[0,0,1]
	ds_read_b128 v[90:93], v185 offset:36864
	ds_read_b128 v[94:97], v186 offset:36864
	s_waitcnt lgkmcnt(4)
	v_mfma_scale_f32_32x32x64_f8f6f4 v[114:129], v[82:89], v[138:145], v[114:129], v194, v193 op_sel_hi:[0,0,0]
	v_exp_f32_e32 v0, v66
	v_exp_f32_e32 v177, v67
	v_exp_f32_e32 v179, v68
	v_exp_f32_e32 v254, v69
	v_add_f32_e32 v219, v0, v219
	v_add_f32_e32 v219, v177, v219
	v_cvt_pk_fp8_f32 v250, v0, v177
	v_add_f32_e32 v219, v179, v219
	v_add_f32_e32 v219, v254, v219
	v_cvt_pk_fp8_f32 v250, v179, v254 op_sel:[0,0,1]
	s_waitcnt lgkmcnt(2)
	v_mfma_scale_f32_32x32x64_f8f6f4 v[98:113], v[222:229], v[138:145], v[98:113], v194, v193 op_sel_hi:[0,0,0]
	ds_read_b128 v[222:225], v185 offset:38912
	ds_read_b128 v[226:229], v186 offset:38912
	v_exp_f32_e32 v0, v70
	v_exp_f32_e32 v177, v71
	v_exp_f32_e32 v179, v72
	v_exp_f32_e32 v254, v73
	v_add_f32_e32 v219, v0, v219
	v_add_f32_e32 v219, v177, v219
	v_cvt_pk_fp8_f32 v251, v0, v177
	v_add_f32_e32 v219, v179, v219
	v_add_f32_e32 v219, v254, v219
	v_cvt_pk_fp8_f32 v251, v179, v254 op_sel:[0,0,1]
	v_exp_f32_e32 v0, v74
	v_exp_f32_e32 v177, v75
	v_exp_f32_e32 v179, v76
	v_exp_f32_e32 v254, v77
	v_add_f32_e32 v219, v0, v219
	v_add_f32_e32 v219, v177, v219
	v_cvt_pk_fp8_f32 v252, v0, v177
	v_add_f32_e32 v219, v179, v219
	v_add_f32_e32 v219, v254, v219
	v_cvt_pk_fp8_f32 v252, v179, v254 op_sel:[0,0,1]
	s_waitcnt lgkmcnt(2)
	v_mfma_scale_f32_32x32x64_f8f6f4 v[114:129], v[90:97], v[130:137], v[114:129], v194, v193 op_sel_hi:[0,0,0]
	v_exp_f32_e32 v0, v78
	v_exp_f32_e32 v177, v79
	v_exp_f32_e32 v179, v80
	v_exp_f32_e32 v254, v81
	v_add_f32_e32 v219, v0, v219
	v_add_f32_e32 v219, v177, v219
	v_cvt_pk_fp8_f32 v253, v0, v177
	v_add_f32_e32 v219, v179, v219
	v_add_f32_e32 v219, v254, v219
	v_cvt_pk_fp8_f32 v253, v179, v254 op_sel:[0,0,1]
	ds_read_b128 v[90:93], v185 offset:0
	ds_read_b128 v[94:97], v186 offset:0
	ds_read_b128 v[82:85], v185 offset:2048
	ds_read_b128 v[86:89], v186 offset:2048
	ds_read_b128 v[74:77], v185 offset:4096
	ds_read_b128 v[78:81], v186 offset:4096
	ds_read_b128 v[66:69], v185 offset:6144
	ds_read_b128 v[70:73], v186 offset:6144
	s_waitcnt lgkmcnt(8)
	v_mfma_scale_f32_32x32x64_f8f6f4 v[98:113], v[222:229], v[130:137], v[98:113], v194, v193 op_sel_hi:[0,0,0]
	v_mov_b32_e32 v0, v219
	s_nop 1
	v_permlane32_swap_b32_e32 v219, v0
	v_add_f32_e32 v219, v219, v0
	v_fma_f32 v209, v209, v218, v219
	v_max_f32_e32 v177, v114, v115
	v_max3_f32 v177, v177, v116, v117
	v_max3_f32 v177, v177, v118, v119
	v_max3_f32 v177, v177, v120, v121
	v_max3_f32 v177, v177, v122, v123
	v_max3_f32 v177, v177, v124, v125
	v_max3_f32 v177, v177, v126, v127
	v_max3_f32 v177, v177, v128, v129
	s_waitcnt lgkmcnt(6)
	v_mfma_scale_f32_32x32x64_f8f6f4 v[50:65], v[246:253], v[90:97], v[50:65], v194, v194 op_sel_hi:[0,0,0]
	s_waitcnt lgkmcnt(4)
	v_mfma_scale_f32_32x32x64_f8f6f4 v[34:49], v[246:253], v[82:89], v[34:49], v194, v194 op_sel_hi:[0,0,0]
	s_waitcnt vmcnt(0)
	s_waitcnt lgkmcnt(0)
	s_barrier
	s_add_i32 m0, s98, 0x0
	s_nop 0
	global_load_lds_dwordx4 v176, s[18:19]
	s_add_i32 m0, s98, 0x4000
	s_nop 0
	global_load_lds_dwordx4 v178, s[16:17]
	v_add_u32_e32 v176, 0x2000, v176
	v_add_u32_e32 v178, 0x20000, v178
	s_waitcnt lgkmcnt(2)
	v_mfma_scale_f32_32x32x64_f8f6f4 v[18:33], v[246:253], v[74:81], v[18:33], v194, v194 op_sel_hi:[0,0,0]
	s_waitcnt lgkmcnt(0)
	v_mfma_scale_f32_32x32x64_f8f6f4 v[2:17], v[246:253], v[66:73], v[2:17], v194, v194 op_sel_hi:[0,0,0]
	v_max_f32_e32 v0, v98, v99
	v_max3_f32 v0, v0, v100, v101
	v_max3_f32 v0, v0, v102, v103
	v_max3_f32 v0, v0, v104, v105
	v_max3_f32 v0, v0, v106, v107
	v_max3_f32 v0, v0, v108, v109
	v_max3_f32 v0, v0, v110, v111
	v_max3_f32 v0, v0, v112, v113
	v_max_f32_e32 v177, v177, v0
	v_mov_b32_e32 v0, v177
	v_mov_b32_e32 v221, 1.0
	s_nop 0
	v_permlane32_swap_b32_e32 v177, v0
	v_max_f32_e32 v177, v177, v0
	v_cmp_ge_f32_e32 vcc, s90, v177
	s_cmp_eq_u64 vcc, exec
	s_cbranch_scc0 .Lmla_q0_newmax
